# v26 + P4: workgroups with only three GEMM units start 8 us late (de-synchronises the epilogue store bursts)
# baseline (speedup 1.0000x reference)
.LBB0_382:
	s_cmp_lt_i32 s90, 5
	s_cselect_b64 s[0:1], -1, 0
	s_cmp_gt_i32 s91, 4
	s_cselect_b64 s[2:3], -1, 0
	s_and_b64 s[0:1], s[0:1], s[2:3]
	s_andn2_b64 vcc, exec, s[0:1]
	s_cbranch_vccnz .LBB0_850
	s_cmpk_lt_u32 s24, 90
	s_cbranch_scc1 .Lp4_nodelay
	s_sleep 127
	s_sleep 127
.Lp4_nodelay:
	s_cmpk_lt_i32 s24, 0x35a
	s_cselect_b64 s[0:1], -1, 0
	v_readfirstlane_b32 s4, v0
	s_and_b64 vcc, exec, s[0:1]
	v_mbcnt_lo_u32_b32 v1, -1, 0
	v_mbcnt_hi_u32_b32 v1, -1, v1
	s_cbranch_vccz .LBB0_385
	s_ashr_i32 s2, s24, 31
	s_lshr_b32 s2, s2, 29
	s_add_i32 s2, s24, s2
	s_and_b32 s3, s2, -8
	s_sub_i32 s3, s24, s3
	s_mul_i32 s6, s3, 0x6b
	s_add_i32 s6, s6, 2
	s_ashr_i32 s2, s2, 3
	s_mul_i32 s5, s3, 0x6c
	s_cmp_lt_i32 s3, 2
	s_cselect_b32 s3, s5, s6
	s_add_i32 s3, s3, s2
	s_mul_hi_i32 s2, s3, 0x4ec4ec4f
	s_lshr_b32 s5, s2, 31
	s_ashr_i32 s2, s2, 5
	s_add_i32 s2, s2, s5
	s_lshl_b32 s5, s2, 3
	s_sub_i32 s6, 0x42, s5
	s_mulk_i32 s2, 0x68
	s_min_u32 s7, s6, 8
	s_sub_i32 s8, s3, s2
	s_sext_i32_i8 s2, s8
	s_waitcnt lgkmcnt(0)
	v_cvt_f32_ubyte0_e32 v3, s7
	v_cvt_f32_i32_e32 v2, s2
	v_rcp_iflag_f32_e32 v4, v3
	s_ashr_i32 s2, s2, 30
	s_or_b32 s6, s2, 1
	v_mul_f32_e32 v4, v2, v4
	v_trunc_f32_e32 v4, v4
	v_fma_f32 v2, -v4, v3, v2
	v_cvt_i32_f32_e32 v4, v4
	v_cmp_ge_f32_e64 s[2:3], |v2|, v3
	s_and_b64 s[2:3], s[2:3], exec
	s_cselect_b32 s2, s6, 0
	v_readfirstlane_b32 s3, v4
	s_add_i32 s2, s3, s2
	s_sext_i32_i8 s6, s2
	s_mul_i32 s2, s2, s7
	s_sub_i32 s2, s8, s2
	s_sext_i32_i8 s2, s2
	s_add_i32 s84, s5, s2
